# GEMM1 rope epilogue: lane^32 exchange done with v_permlane32_swap + v_cndmask on the VALU instead of 32 ds_bpermute groups with lgkmcnt(0) waits
# speedup vs baseline: 1.0113x; 1.0007x over previous
.LBB0_500:
	s_and_b64 vcc, exec, s[40:41]
	s_cbranch_vccnz .LBB0_502
	v_mbcnt_hi_u32_b32 v42, -1, v194
	v_and_b32_e32 v62, 64, v42
	v_xor_b32_e32 v43, 32, v42
	v_add_u32_e32 v62, 64, v62
	v_cmp_lt_i32_e32 vcc, v43, v62
	s_nop 1
	v_cndmask_b32_e32 v42, v42, v43, vcc
	v_lshlrev_b32_e32 v66, 2, v42
	v_mov_b32_e32 v236, v146
	v_mov_b32_e32 v237, v146
	v_mov_b32_e32 v238, v147
	v_mov_b32_e32 v239, v147
	v_mov_b32_e32 v240, v148
	v_mov_b32_e32 v241, v148
	v_mov_b32_e32 v242, v149
	v_mov_b32_e32 v243, v149
	v_permlane32_swap_b32_e32 v236, v237
	v_permlane32_swap_b32_e32 v238, v239
	v_permlane32_swap_b32_e32 v240, v241
	v_permlane32_swap_b32_e32 v242, v243
	s_nop 0
	v_cndmask_b32_e64 v42, v237, v236, s[36:37]
	v_cndmask_b32_e64 v43, v239, v238, s[36:37]
	v_cndmask_b32_e64 v62, v241, v240, s[36:37]
	v_cndmask_b32_e64 v63, v243, v242, s[36:37]
	s_waitcnt lgkmcnt(0)
	v_pk_mul_f32 v[42:43], v[68:69], v[42:43]
	s_nop 0
	v_cndmask_b32_e64 v43, -v43, v43, s[36:37]
	v_pk_mul_f32 v[62:63], v[64:65], v[62:63]
	v_cndmask_b32_e64 v42, -v42, v42, s[36:37]
	v_cndmask_b32_e64 v63, -v63, v63, s[36:37]
	v_cndmask_b32_e64 v62, -v62, v62, s[36:37]
	v_pk_fma_f32 v[148:149], v[148:149], v[60:61], v[62:63]
	v_pk_fma_f32 v[146:147], v[146:147], v[56:57], v[42:43]
	v_mov_b32_e32 v236, v142
	v_mov_b32_e32 v237, v142
	v_mov_b32_e32 v238, v143
	v_mov_b32_e32 v239, v143
	v_mov_b32_e32 v240, v144
	v_mov_b32_e32 v241, v144
	v_mov_b32_e32 v242, v145
	v_mov_b32_e32 v243, v145
	v_permlane32_swap_b32_e32 v236, v237
	v_permlane32_swap_b32_e32 v238, v239
	v_permlane32_swap_b32_e32 v240, v241
	v_permlane32_swap_b32_e32 v242, v243
	s_nop 0
	v_cndmask_b32_e64 v42, v237, v236, s[36:37]
	v_cndmask_b32_e64 v43, v239, v238, s[36:37]
	v_cndmask_b32_e64 v62, v241, v240, s[36:37]
	v_cndmask_b32_e64 v63, v243, v242, s[36:37]
	s_waitcnt lgkmcnt(0)
	v_pk_mul_f32 v[42:43], v[46:47], v[42:43]
	s_nop 0
	v_cndmask_b32_e64 v43, -v43, v43, s[36:37]
	v_pk_mul_f32 v[62:63], v[58:59], v[62:63]
	v_cndmask_b32_e64 v42, -v42, v42, s[36:37]
	v_cndmask_b32_e64 v63, -v63, v63, s[36:37]
	v_cndmask_b32_e64 v62, -v62, v62, s[36:37]
	v_pk_fma_f32 v[144:145], v[144:145], v[44:45], v[62:63]
	v_pk_fma_f32 v[142:143], v[142:143], v[40:41], v[42:43]

.LBB0_504:
	s_and_b64 vcc, exec, s[40:41]
	s_cbranch_vccnz .LBB0_506
	v_mbcnt_hi_u32_b32 v63, -1, v194
	v_and_b32_e32 v143, 64, v63
	v_xor_b32_e32 v142, 32, v63
	v_add_u32_e32 v143, 64, v143
	v_cmp_lt_i32_e32 vcc, v142, v143
	s_nop 1
	v_cndmask_b32_e32 v63, v63, v142, vcc
	v_lshlrev_b32_e32 v63, 2, v63
	v_mov_b32_e32 v236, v138
	v_mov_b32_e32 v237, v138
	v_mov_b32_e32 v238, v139
	v_mov_b32_e32 v239, v139
	v_mov_b32_e32 v240, v140
	v_mov_b32_e32 v241, v140
	v_mov_b32_e32 v242, v141
	v_mov_b32_e32 v243, v141
	v_permlane32_swap_b32_e32 v236, v237
	v_permlane32_swap_b32_e32 v238, v239
	v_permlane32_swap_b32_e32 v240, v241
	v_permlane32_swap_b32_e32 v242, v243
	s_nop 0
	v_cndmask_b32_e64 v142, v237, v236, s[36:37]
	v_cndmask_b32_e64 v143, v239, v238, s[36:37]
	v_cndmask_b32_e64 v144, v241, v240, s[36:37]
	v_cndmask_b32_e64 v145, v243, v242, s[36:37]
	s_waitcnt lgkmcnt(0)
	v_pk_mul_f32 v[142:143], v[68:69], v[142:143]
	s_nop 0
	v_cndmask_b32_e64 v143, -v143, v143, s[36:37]
	v_pk_mul_f32 v[144:145], v[64:65], v[144:145]
	v_cndmask_b32_e64 v142, -v142, v142, s[36:37]
	v_cndmask_b32_e64 v145, -v145, v145, s[36:37]
	v_cndmask_b32_e64 v144, -v144, v144, s[36:37]
	v_pk_fma_f32 v[140:141], v[140:141], v[60:61], v[144:145]
	v_pk_fma_f32 v[138:139], v[138:139], v[56:57], v[142:143]
	v_mov_b32_e32 v236, v134
	v_mov_b32_e32 v237, v134
	v_mov_b32_e32 v238, v135
	v_mov_b32_e32 v239, v135
	v_mov_b32_e32 v240, v136
	v_mov_b32_e32 v241, v136
	v_mov_b32_e32 v242, v137
	v_mov_b32_e32 v243, v137
	v_permlane32_swap_b32_e32 v236, v237
	v_permlane32_swap_b32_e32 v238, v239
	v_permlane32_swap_b32_e32 v240, v241
	v_permlane32_swap_b32_e32 v242, v243
	s_nop 0
	v_cndmask_b32_e64 v142, v237, v236, s[36:37]
	v_cndmask_b32_e64 v143, v239, v238, s[36:37]
	v_cndmask_b32_e64 v144, v241, v240, s[36:37]
	v_cndmask_b32_e64 v145, v243, v242, s[36:37]
	s_waitcnt lgkmcnt(0)
	v_pk_mul_f32 v[142:143], v[46:47], v[142:143]
	s_nop 0
	v_cndmask_b32_e64 v143, -v143, v143, s[36:37]
	v_pk_mul_f32 v[144:145], v[58:59], v[144:145]
	v_cndmask_b32_e64 v142, -v142, v142, s[36:37]
	v_cndmask_b32_e64 v145, -v145, v145, s[36:37]
	v_cndmask_b32_e64 v144, -v144, v144, s[36:37]
	v_pk_fma_f32 v[136:137], v[136:137], v[44:45], v[144:145]
	v_pk_fma_f32 v[134:135], v[134:135], v[40:41], v[142:143]

.LBB0_509:
	v_mbcnt_hi_u32_b32 v42, -1, v194
	v_and_b32_e32 v62, 64, v42
	v_xor_b32_e32 v43, 32, v42
	v_add_u32_e32 v62, 64, v62
	v_cmp_lt_i32_e32 vcc, v43, v62
	s_nop 1
	v_cndmask_b32_e32 v42, v42, v43, vcc
	v_lshlrev_b32_e32 v135, 2, v42
	v_mov_b32_e32 v236, v130
	v_mov_b32_e32 v237, v130
	v_mov_b32_e32 v238, v131
	v_mov_b32_e32 v239, v131
	v_mov_b32_e32 v240, v132
	v_mov_b32_e32 v241, v132
	v_mov_b32_e32 v242, v133
	v_mov_b32_e32 v243, v133
	v_permlane32_swap_b32_e32 v236, v237
	v_permlane32_swap_b32_e32 v238, v239
	v_permlane32_swap_b32_e32 v240, v241
	v_permlane32_swap_b32_e32 v242, v243
	s_nop 0
	v_cndmask_b32_e64 v42, v237, v236, s[36:37]
	v_cndmask_b32_e64 v43, v239, v238, s[36:37]
	v_cndmask_b32_e64 v62, v241, v240, s[36:37]
	v_cndmask_b32_e64 v63, v243, v242, s[36:37]
	s_waitcnt lgkmcnt(0)
	v_pk_mul_f32 v[42:43], v[68:69], v[42:43]
	s_nop 0
	v_cndmask_b32_e64 v43, -v43, v43, s[36:37]
	v_pk_mul_f32 v[62:63], v[64:65], v[62:63]
	v_cndmask_b32_e64 v42, -v42, v42, s[36:37]
	v_cndmask_b32_e64 v63, -v63, v63, s[36:37]
	v_cndmask_b32_e64 v62, -v62, v62, s[36:37]
	v_pk_fma_f32 v[132:133], v[132:133], v[60:61], v[62:63]
	v_pk_fma_f32 v[130:131], v[130:131], v[56:57], v[42:43]
	v_mov_b32_e32 v236, v126
	v_mov_b32_e32 v237, v126
	v_mov_b32_e32 v238, v127
	v_mov_b32_e32 v239, v127
	v_mov_b32_e32 v240, v128
	v_mov_b32_e32 v241, v128
	v_mov_b32_e32 v242, v129
	v_mov_b32_e32 v243, v129
	v_permlane32_swap_b32_e32 v236, v237
	v_permlane32_swap_b32_e32 v238, v239
	v_permlane32_swap_b32_e32 v240, v241
	v_permlane32_swap_b32_e32 v242, v243
	s_nop 0
	v_cndmask_b32_e64 v42, v237, v236, s[36:37]
	v_cndmask_b32_e64 v43, v239, v238, s[36:37]
	v_cndmask_b32_e64 v62, v241, v240, s[36:37]
	v_cndmask_b32_e64 v63, v243, v242, s[36:37]
	s_waitcnt lgkmcnt(0)
	v_pk_mul_f32 v[42:43], v[46:47], v[42:43]
	s_nop 0
	v_cndmask_b32_e64 v43, -v43, v43, s[36:37]
	v_pk_mul_f32 v[62:63], v[58:59], v[62:63]
	v_cndmask_b32_e64 v42, -v42, v42, s[36:37]
	v_cndmask_b32_e64 v63, -v63, v63, s[36:37]
	v_cndmask_b32_e64 v62, -v62, v62, s[36:37]
	v_pk_fma_f32 v[128:129], v[128:129], v[44:45], v[62:63]
	v_pk_fma_f32 v[126:127], v[126:127], v[40:41], v[42:43]

.LBB0_512:
	s_and_b64 vcc, exec, s[40:41]
	s_cbranch_vccnz .LBB0_514
	v_mbcnt_hi_u32_b32 v63, -1, v194
	v_and_b32_e32 v127, 64, v63
	v_xor_b32_e32 v126, 32, v63
	v_add_u32_e32 v127, 64, v127
	v_cmp_lt_i32_e32 vcc, v126, v127
	s_nop 1
	v_cndmask_b32_e32 v63, v63, v126, vcc
	v_lshlrev_b32_e32 v63, 2, v63
	v_mov_b32_e32 v236, v122
	v_mov_b32_e32 v237, v122
	v_mov_b32_e32 v238, v123
	v_mov_b32_e32 v239, v123
	v_mov_b32_e32 v240, v124
	v_mov_b32_e32 v241, v124
	v_mov_b32_e32 v242, v125
	v_mov_b32_e32 v243, v125
	v_permlane32_swap_b32_e32 v236, v237
	v_permlane32_swap_b32_e32 v238, v239
	v_permlane32_swap_b32_e32 v240, v241
	v_permlane32_swap_b32_e32 v242, v243
	s_nop 0
	v_cndmask_b32_e64 v126, v237, v236, s[36:37]
	v_cndmask_b32_e64 v127, v239, v238, s[36:37]
	v_cndmask_b32_e64 v128, v241, v240, s[36:37]
	v_cndmask_b32_e64 v129, v243, v242, s[36:37]
	s_waitcnt lgkmcnt(0)
	v_pk_mul_f32 v[126:127], v[68:69], v[126:127]
	s_nop 0
	v_cndmask_b32_e64 v127, -v127, v127, s[36:37]
	v_pk_mul_f32 v[128:129], v[64:65], v[128:129]
	v_cndmask_b32_e64 v126, -v126, v126, s[36:37]
	v_cndmask_b32_e64 v129, -v129, v129, s[36:37]
	v_cndmask_b32_e64 v128, -v128, v128, s[36:37]
	v_pk_fma_f32 v[124:125], v[124:125], v[60:61], v[128:129]
	v_pk_fma_f32 v[122:123], v[122:123], v[56:57], v[126:127]
	v_mov_b32_e32 v236, v118
	v_mov_b32_e32 v237, v118
	v_mov_b32_e32 v238, v119
	v_mov_b32_e32 v239, v119
	v_mov_b32_e32 v240, v120
	v_mov_b32_e32 v241, v120
	v_mov_b32_e32 v242, v121
	v_mov_b32_e32 v243, v121
	v_permlane32_swap_b32_e32 v236, v237
	v_permlane32_swap_b32_e32 v238, v239
	v_permlane32_swap_b32_e32 v240, v241
	v_permlane32_swap_b32_e32 v242, v243
	s_nop 0
	v_cndmask_b32_e64 v126, v237, v236, s[36:37]
	v_cndmask_b32_e64 v127, v239, v238, s[36:37]
	v_cndmask_b32_e64 v128, v241, v240, s[36:37]
	v_cndmask_b32_e64 v129, v243, v242, s[36:37]
	s_waitcnt lgkmcnt(0)
	v_pk_mul_f32 v[126:127], v[46:47], v[126:127]
	s_nop 0
	v_cndmask_b32_e64 v127, -v127, v127, s[36:37]
	v_pk_mul_f32 v[128:129], v[58:59], v[128:129]
	v_cndmask_b32_e64 v126, -v126, v126, s[36:37]
	v_cndmask_b32_e64 v129, -v129, v129, s[36:37]
	v_cndmask_b32_e64 v128, -v128, v128, s[36:37]
	v_pk_fma_f32 v[120:121], v[120:121], v[44:45], v[128:129]
	v_pk_fma_f32 v[118:119], v[118:119], v[40:41], v[126:127]

.LBB0_517:
	v_mbcnt_hi_u32_b32 v42, -1, v194
	v_and_b32_e32 v62, 64, v42
	v_xor_b32_e32 v43, 32, v42
	v_add_u32_e32 v62, 64, v62
	v_cmp_lt_i32_e32 vcc, v43, v62
	s_nop 1
	v_cndmask_b32_e32 v42, v42, v43, vcc
	v_lshlrev_b32_e32 v119, 2, v42
	v_mov_b32_e32 v236, v114
	v_mov_b32_e32 v237, v114
	v_mov_b32_e32 v238, v115
	v_mov_b32_e32 v239, v115
	v_mov_b32_e32 v240, v116
	v_mov_b32_e32 v241, v116
	v_mov_b32_e32 v242, v117
	v_mov_b32_e32 v243, v117
	v_permlane32_swap_b32_e32 v236, v237
	v_permlane32_swap_b32_e32 v238, v239
	v_permlane32_swap_b32_e32 v240, v241
	v_permlane32_swap_b32_e32 v242, v243
	s_nop 0
	v_cndmask_b32_e64 v42, v237, v236, s[36:37]
	v_cndmask_b32_e64 v43, v239, v238, s[36:37]
	v_cndmask_b32_e64 v62, v241, v240, s[36:37]
	v_cndmask_b32_e64 v63, v243, v242, s[36:37]
	s_waitcnt lgkmcnt(0)
	v_pk_mul_f32 v[42:43], v[68:69], v[42:43]
	s_nop 0
	v_cndmask_b32_e64 v43, -v43, v43, s[36:37]
	v_pk_mul_f32 v[62:63], v[64:65], v[62:63]
	v_cndmask_b32_e64 v42, -v42, v42, s[36:37]
	v_cndmask_b32_e64 v63, -v63, v63, s[36:37]
	v_cndmask_b32_e64 v62, -v62, v62, s[36:37]
	v_pk_fma_f32 v[116:117], v[116:117], v[60:61], v[62:63]
	v_pk_fma_f32 v[114:115], v[114:115], v[56:57], v[42:43]
	v_mov_b32_e32 v236, v110
	v_mov_b32_e32 v237, v110
	v_mov_b32_e32 v238, v111
	v_mov_b32_e32 v239, v111
	v_mov_b32_e32 v240, v112
	v_mov_b32_e32 v241, v112
	v_mov_b32_e32 v242, v113
	v_mov_b32_e32 v243, v113
	v_permlane32_swap_b32_e32 v236, v237
	v_permlane32_swap_b32_e32 v238, v239
	v_permlane32_swap_b32_e32 v240, v241
	v_permlane32_swap_b32_e32 v242, v243
	s_nop 0
	v_cndmask_b32_e64 v42, v237, v236, s[36:37]
	v_cndmask_b32_e64 v43, v239, v238, s[36:37]
	v_cndmask_b32_e64 v62, v241, v240, s[36:37]
	v_cndmask_b32_e64 v63, v243, v242, s[36:37]
	s_waitcnt lgkmcnt(0)
	v_pk_mul_f32 v[42:43], v[46:47], v[42:43]
	s_nop 0
	v_cndmask_b32_e64 v43, -v43, v43, s[36:37]
	v_pk_mul_f32 v[62:63], v[58:59], v[62:63]
	v_cndmask_b32_e64 v42, -v42, v42, s[36:37]
	v_cndmask_b32_e64 v63, -v63, v63, s[36:37]
	v_cndmask_b32_e64 v62, -v62, v62, s[36:37]
	v_pk_fma_f32 v[112:113], v[112:113], v[44:45], v[62:63]
	v_pk_fma_f32 v[110:111], v[110:111], v[40:41], v[42:43]

.LBB0_520:
	s_and_b64 vcc, exec, s[40:41]
	s_cbranch_vccnz .LBB0_522
	v_mbcnt_hi_u32_b32 v63, -1, v194
	v_and_b32_e32 v111, 64, v63
	v_xor_b32_e32 v110, 32, v63
	v_add_u32_e32 v111, 64, v111
	v_cmp_lt_i32_e32 vcc, v110, v111
	s_nop 1
	v_cndmask_b32_e32 v63, v63, v110, vcc
	v_lshlrev_b32_e32 v63, 2, v63
	v_mov_b32_e32 v236, v106
	v_mov_b32_e32 v237, v106
	v_mov_b32_e32 v238, v107
	v_mov_b32_e32 v239, v107
	v_mov_b32_e32 v240, v108
	v_mov_b32_e32 v241, v108
	v_mov_b32_e32 v242, v109
	v_mov_b32_e32 v243, v109
	v_permlane32_swap_b32_e32 v236, v237
	v_permlane32_swap_b32_e32 v238, v239
	v_permlane32_swap_b32_e32 v240, v241
	v_permlane32_swap_b32_e32 v242, v243
	s_nop 0
	v_cndmask_b32_e64 v110, v237, v236, s[36:37]
	v_cndmask_b32_e64 v111, v239, v238, s[36:37]
	v_cndmask_b32_e64 v112, v241, v240, s[36:37]
	v_cndmask_b32_e64 v113, v243, v242, s[36:37]
	s_waitcnt lgkmcnt(0)
	v_pk_mul_f32 v[110:111], v[68:69], v[110:111]
	s_nop 0
	v_cndmask_b32_e64 v111, -v111, v111, s[36:37]
	v_pk_mul_f32 v[112:113], v[64:65], v[112:113]
	v_cndmask_b32_e64 v110, -v110, v110, s[36:37]
	v_cndmask_b32_e64 v113, -v113, v113, s[36:37]
	v_cndmask_b32_e64 v112, -v112, v112, s[36:37]
	v_pk_fma_f32 v[108:109], v[108:109], v[60:61], v[112:113]
	v_pk_fma_f32 v[106:107], v[106:107], v[56:57], v[110:111]
	v_mov_b32_e32 v236, v102
	v_mov_b32_e32 v237, v102
	v_mov_b32_e32 v238, v103
	v_mov_b32_e32 v239, v103
	v_mov_b32_e32 v240, v104
	v_mov_b32_e32 v241, v104
	v_mov_b32_e32 v242, v105
	v_mov_b32_e32 v243, v105
	v_permlane32_swap_b32_e32 v236, v237
	v_permlane32_swap_b32_e32 v238, v239
	v_permlane32_swap_b32_e32 v240, v241
	v_permlane32_swap_b32_e32 v242, v243
	s_nop 0
	v_cndmask_b32_e64 v110, v237, v236, s[36:37]
	v_cndmask_b32_e64 v111, v239, v238, s[36:37]
	v_cndmask_b32_e64 v112, v241, v240, s[36:37]
	v_cndmask_b32_e64 v113, v243, v242, s[36:37]
	s_waitcnt lgkmcnt(0)
	v_pk_mul_f32 v[110:111], v[46:47], v[110:111]
	s_nop 0
	v_cndmask_b32_e64 v111, -v111, v111, s[36:37]
	v_pk_mul_f32 v[112:113], v[58:59], v[112:113]
	v_cndmask_b32_e64 v110, -v110, v110, s[36:37]
	v_cndmask_b32_e64 v113, -v113, v113, s[36:37]
	v_cndmask_b32_e64 v112, -v112, v112, s[36:37]
	v_pk_fma_f32 v[104:105], v[104:105], v[44:45], v[112:113]
	v_pk_fma_f32 v[102:103], v[102:103], v[40:41], v[110:111]

.LBB0_525:
	v_mbcnt_hi_u32_b32 v42, -1, v194
	v_and_b32_e32 v62, 64, v42
	v_xor_b32_e32 v43, 32, v42
	v_add_u32_e32 v62, 64, v62
	v_cmp_lt_i32_e32 vcc, v43, v62
	s_nop 1
	v_cndmask_b32_e32 v42, v42, v43, vcc
	v_lshlrev_b32_e32 v103, 2, v42
	v_mov_b32_e32 v236, v98
	v_mov_b32_e32 v237, v98
	v_mov_b32_e32 v238, v99
	v_mov_b32_e32 v239, v99
	v_mov_b32_e32 v240, v100
	v_mov_b32_e32 v241, v100
	v_mov_b32_e32 v242, v101
	v_mov_b32_e32 v243, v101
	v_permlane32_swap_b32_e32 v236, v237
	v_permlane32_swap_b32_e32 v238, v239
	v_permlane32_swap_b32_e32 v240, v241
	v_permlane32_swap_b32_e32 v242, v243
	s_nop 0
	v_cndmask_b32_e64 v42, v237, v236, s[36:37]
	v_cndmask_b32_e64 v43, v239, v238, s[36:37]
	v_cndmask_b32_e64 v62, v241, v240, s[36:37]
	v_cndmask_b32_e64 v63, v243, v242, s[36:37]
	s_waitcnt lgkmcnt(0)
	v_pk_mul_f32 v[42:43], v[68:69], v[42:43]
	s_nop 0
	v_cndmask_b32_e64 v43, -v43, v43, s[36:37]
	v_pk_mul_f32 v[62:63], v[64:65], v[62:63]
	v_cndmask_b32_e64 v42, -v42, v42, s[36:37]
	v_cndmask_b32_e64 v63, -v63, v63, s[36:37]
	v_cndmask_b32_e64 v62, -v62, v62, s[36:37]
	v_pk_fma_f32 v[100:101], v[100:101], v[60:61], v[62:63]
	v_pk_fma_f32 v[98:99], v[98:99], v[56:57], v[42:43]
	v_mov_b32_e32 v236, v94
	v_mov_b32_e32 v237, v94
	v_mov_b32_e32 v238, v95
	v_mov_b32_e32 v239, v95
	v_mov_b32_e32 v240, v96
	v_mov_b32_e32 v241, v96
	v_mov_b32_e32 v242, v97
	v_mov_b32_e32 v243, v97
	v_permlane32_swap_b32_e32 v236, v237
	v_permlane32_swap_b32_e32 v238, v239
	v_permlane32_swap_b32_e32 v240, v241
	v_permlane32_swap_b32_e32 v242, v243
	s_nop 0
	v_cndmask_b32_e64 v42, v237, v236, s[36:37]
	v_cndmask_b32_e64 v43, v239, v238, s[36:37]
	v_cndmask_b32_e64 v62, v241, v240, s[36:37]
	v_cndmask_b32_e64 v63, v243, v242, s[36:37]
	s_waitcnt lgkmcnt(0)
	v_pk_mul_f32 v[42:43], v[46:47], v[42:43]
	s_nop 0
	v_cndmask_b32_e64 v43, -v43, v43, s[36:37]
	v_pk_mul_f32 v[62:63], v[58:59], v[62:63]
	v_cndmask_b32_e64 v42, -v42, v42, s[36:37]
	v_cndmask_b32_e64 v63, -v63, v63, s[36:37]
	v_cndmask_b32_e64 v62, -v62, v62, s[36:37]
	v_pk_fma_f32 v[96:97], v[96:97], v[44:45], v[62:63]
	v_pk_fma_f32 v[94:95], v[94:95], v[40:41], v[42:43]

.LBB0_528:
	s_and_b64 vcc, exec, s[40:41]
	s_cbranch_vccnz .LBB0_530
	v_mbcnt_hi_u32_b32 v63, -1, v194
	v_and_b32_e32 v95, 64, v63
	v_xor_b32_e32 v94, 32, v63
	v_add_u32_e32 v95, 64, v95
	v_cmp_lt_i32_e32 vcc, v94, v95
	s_nop 1
	v_cndmask_b32_e32 v63, v63, v94, vcc
	v_lshlrev_b32_e32 v63, 2, v63
	v_mov_b32_e32 v236, v90
	v_mov_b32_e32 v237, v90
	v_mov_b32_e32 v238, v91
	v_mov_b32_e32 v239, v91
	v_mov_b32_e32 v240, v92
	v_mov_b32_e32 v241, v92
	v_mov_b32_e32 v242, v93
	v_mov_b32_e32 v243, v93
	v_permlane32_swap_b32_e32 v236, v237
	v_permlane32_swap_b32_e32 v238, v239
	v_permlane32_swap_b32_e32 v240, v241
	v_permlane32_swap_b32_e32 v242, v243
	s_nop 0
	v_cndmask_b32_e64 v94, v237, v236, s[36:37]
	v_cndmask_b32_e64 v95, v239, v238, s[36:37]
	v_cndmask_b32_e64 v96, v241, v240, s[36:37]
	v_cndmask_b32_e64 v97, v243, v242, s[36:37]
	s_waitcnt lgkmcnt(0)
	v_pk_mul_f32 v[94:95], v[68:69], v[94:95]
	s_nop 0
	v_cndmask_b32_e64 v95, -v95, v95, s[36:37]
	v_pk_mul_f32 v[96:97], v[64:65], v[96:97]
	v_cndmask_b32_e64 v94, -v94, v94, s[36:37]
	v_cndmask_b32_e64 v97, -v97, v97, s[36:37]
	v_cndmask_b32_e64 v96, -v96, v96, s[36:37]
	v_pk_fma_f32 v[92:93], v[92:93], v[60:61], v[96:97]
	v_pk_fma_f32 v[90:91], v[90:91], v[56:57], v[94:95]
	v_mov_b32_e32 v236, v86
	v_mov_b32_e32 v237, v86
	v_mov_b32_e32 v238, v87
	v_mov_b32_e32 v239, v87
	v_mov_b32_e32 v240, v88
	v_mov_b32_e32 v241, v88
	v_mov_b32_e32 v242, v89
	v_mov_b32_e32 v243, v89
	v_permlane32_swap_b32_e32 v236, v237
	v_permlane32_swap_b32_e32 v238, v239
	v_permlane32_swap_b32_e32 v240, v241
	v_permlane32_swap_b32_e32 v242, v243
	s_nop 0
	v_cndmask_b32_e64 v94, v237, v236, s[36:37]
	v_cndmask_b32_e64 v95, v239, v238, s[36:37]
	v_cndmask_b32_e64 v96, v241, v240, s[36:37]
	v_cndmask_b32_e64 v97, v243, v242, s[36:37]
	s_waitcnt lgkmcnt(0)
	v_pk_mul_f32 v[94:95], v[46:47], v[94:95]
	s_nop 0
	v_cndmask_b32_e64 v95, -v95, v95, s[36:37]
	v_pk_mul_f32 v[96:97], v[58:59], v[96:97]
	v_cndmask_b32_e64 v94, -v94, v94, s[36:37]
	v_cndmask_b32_e64 v97, -v97, v97, s[36:37]
	v_cndmask_b32_e64 v96, -v96, v96, s[36:37]
	v_pk_fma_f32 v[88:89], v[88:89], v[44:45], v[96:97]
	v_pk_fma_f32 v[86:87], v[86:87], v[40:41], v[94:95]

.LBB0_533:
	v_mbcnt_hi_u32_b32 v42, -1, v194
	v_and_b32_e32 v62, 64, v42
	v_xor_b32_e32 v43, 32, v42
	v_add_u32_e32 v62, 64, v62
	v_cmp_lt_i32_e32 vcc, v43, v62
	s_nop 1
	v_cndmask_b32_e32 v42, v42, v43, vcc
	v_lshlrev_b32_e32 v87, 2, v42
	v_mov_b32_e32 v236, v82
	v_mov_b32_e32 v237, v82
	v_mov_b32_e32 v238, v83
	v_mov_b32_e32 v239, v83
	v_mov_b32_e32 v240, v84
	v_mov_b32_e32 v241, v84
	v_mov_b32_e32 v242, v85
	v_mov_b32_e32 v243, v85
	v_permlane32_swap_b32_e32 v236, v237
	v_permlane32_swap_b32_e32 v238, v239
	v_permlane32_swap_b32_e32 v240, v241
	v_permlane32_swap_b32_e32 v242, v243
	s_nop 0
	v_cndmask_b32_e64 v42, v237, v236, s[36:37]
	v_cndmask_b32_e64 v43, v239, v238, s[36:37]
	v_cndmask_b32_e64 v62, v241, v240, s[36:37]
	v_cndmask_b32_e64 v63, v243, v242, s[36:37]
	s_waitcnt lgkmcnt(0)
	v_pk_mul_f32 v[42:43], v[68:69], v[42:43]
	s_nop 0
	v_cndmask_b32_e64 v43, -v43, v43, s[36:37]
	v_pk_mul_f32 v[62:63], v[64:65], v[62:63]
	v_cndmask_b32_e64 v42, -v42, v42, s[36:37]
	v_cndmask_b32_e64 v63, -v63, v63, s[36:37]
	v_cndmask_b32_e64 v62, -v62, v62, s[36:37]
	v_pk_fma_f32 v[84:85], v[84:85], v[60:61], v[62:63]
	v_pk_fma_f32 v[82:83], v[82:83], v[56:57], v[42:43]
	v_mov_b32_e32 v236, v78
	v_mov_b32_e32 v237, v78
	v_mov_b32_e32 v238, v79
	v_mov_b32_e32 v239, v79
	v_mov_b32_e32 v240, v80
	v_mov_b32_e32 v241, v80
	v_mov_b32_e32 v242, v81
	v_mov_b32_e32 v243, v81
	v_permlane32_swap_b32_e32 v236, v237
	v_permlane32_swap_b32_e32 v238, v239
	v_permlane32_swap_b32_e32 v240, v241
	v_permlane32_swap_b32_e32 v242, v243
	s_nop 0
	v_cndmask_b32_e64 v42, v237, v236, s[36:37]
	v_cndmask_b32_e64 v43, v239, v238, s[36:37]
	v_cndmask_b32_e64 v62, v241, v240, s[36:37]
	v_cndmask_b32_e64 v63, v243, v242, s[36:37]
	s_waitcnt lgkmcnt(0)
	v_pk_mul_f32 v[42:43], v[46:47], v[42:43]
	s_nop 0
	v_cndmask_b32_e64 v43, -v43, v43, s[36:37]
	v_pk_mul_f32 v[62:63], v[58:59], v[62:63]
	v_cndmask_b32_e64 v42, -v42, v42, s[36:37]
	v_cndmask_b32_e64 v63, -v63, v63, s[36:37]
	v_cndmask_b32_e64 v62, -v62, v62, s[36:37]
	v_pk_fma_f32 v[80:81], v[80:81], v[44:45], v[62:63]
	v_pk_fma_f32 v[78:79], v[78:79], v[40:41], v[42:43]

.LBB0_536:
	s_and_b64 vcc, exec, s[40:41]
	s_cbranch_vccnz .LBB0_538
	v_mbcnt_hi_u32_b32 v63, -1, v194
	v_and_b32_e32 v79, 64, v63
	v_xor_b32_e32 v78, 32, v63
	v_add_u32_e32 v79, 64, v79
	v_cmp_lt_i32_e32 vcc, v78, v79
	s_nop 1
	v_cndmask_b32_e32 v63, v63, v78, vcc
	v_lshlrev_b32_e32 v63, 2, v63
	v_mov_b32_e32 v236, v74
	v_mov_b32_e32 v237, v74
	v_mov_b32_e32 v238, v75
	v_mov_b32_e32 v239, v75
	v_mov_b32_e32 v240, v76
	v_mov_b32_e32 v241, v76
	v_mov_b32_e32 v242, v77
	v_mov_b32_e32 v243, v77
	v_permlane32_swap_b32_e32 v236, v237
	v_permlane32_swap_b32_e32 v238, v239
	v_permlane32_swap_b32_e32 v240, v241
	v_permlane32_swap_b32_e32 v242, v243
	s_nop 0
	v_cndmask_b32_e64 v78, v237, v236, s[36:37]
	v_cndmask_b32_e64 v79, v239, v238, s[36:37]
	v_cndmask_b32_e64 v80, v241, v240, s[36:37]
	v_cndmask_b32_e64 v81, v243, v242, s[36:37]
	s_waitcnt lgkmcnt(0)
	v_pk_mul_f32 v[78:79], v[68:69], v[78:79]
	s_nop 0
	v_cndmask_b32_e64 v79, -v79, v79, s[36:37]
	v_pk_mul_f32 v[80:81], v[64:65], v[80:81]
	v_cndmask_b32_e64 v78, -v78, v78, s[36:37]
	v_cndmask_b32_e64 v81, -v81, v81, s[36:37]
	v_cndmask_b32_e64 v80, -v80, v80, s[36:37]
	v_pk_fma_f32 v[76:77], v[76:77], v[60:61], v[80:81]
	v_pk_fma_f32 v[74:75], v[74:75], v[56:57], v[78:79]
	v_mov_b32_e32 v236, v70
	v_mov_b32_e32 v237, v70
	v_mov_b32_e32 v238, v71
	v_mov_b32_e32 v239, v71
	v_mov_b32_e32 v240, v72
	v_mov_b32_e32 v241, v72
	v_mov_b32_e32 v242, v73
	v_mov_b32_e32 v243, v73
	v_permlane32_swap_b32_e32 v236, v237
	v_permlane32_swap_b32_e32 v238, v239
	v_permlane32_swap_b32_e32 v240, v241
	v_permlane32_swap_b32_e32 v242, v243
	s_nop 0
	v_cndmask_b32_e64 v78, v237, v236, s[36:37]
	v_cndmask_b32_e64 v79, v239, v238, s[36:37]
	v_cndmask_b32_e64 v80, v241, v240, s[36:37]
	v_cndmask_b32_e64 v81, v243, v242, s[36:37]
	s_waitcnt lgkmcnt(0)
	v_pk_mul_f32 v[78:79], v[46:47], v[78:79]
	s_nop 0
	v_cndmask_b32_e64 v79, -v79, v79, s[36:37]
	v_pk_mul_f32 v[80:81], v[58:59], v[80:81]
	v_cndmask_b32_e64 v78, -v78, v78, s[36:37]
	v_cndmask_b32_e64 v81, -v81, v81, s[36:37]
	v_cndmask_b32_e64 v80, -v80, v80, s[36:37]
	v_pk_fma_f32 v[72:73], v[72:73], v[44:45], v[80:81]
	v_pk_fma_f32 v[70:71], v[70:71], v[40:41], v[78:79]

.LBB0_541:
	v_mbcnt_hi_u32_b32 v42, -1, v194
	v_and_b32_e32 v62, 64, v42
	v_xor_b32_e32 v43, 32, v42
	v_add_u32_e32 v62, 64, v62
	v_cmp_lt_i32_e32 vcc, v43, v62
	s_nop 1
	v_cndmask_b32_e32 v42, v42, v43, vcc
	v_lshlrev_b32_e32 v71, 2, v42
	v_mov_b32_e32 v236, v52
	v_mov_b32_e32 v237, v52
	v_mov_b32_e32 v238, v53
	v_mov_b32_e32 v239, v53
	v_mov_b32_e32 v240, v54
	v_mov_b32_e32 v241, v54
	v_mov_b32_e32 v242, v55
	v_mov_b32_e32 v243, v55
	v_permlane32_swap_b32_e32 v236, v237
	v_permlane32_swap_b32_e32 v238, v239
	v_permlane32_swap_b32_e32 v240, v241
	v_permlane32_swap_b32_e32 v242, v243
	s_nop 0
	v_cndmask_b32_e64 v42, v237, v236, s[36:37]
	v_cndmask_b32_e64 v43, v239, v238, s[36:37]
	v_cndmask_b32_e64 v62, v241, v240, s[36:37]
	v_cndmask_b32_e64 v63, v243, v242, s[36:37]
	s_waitcnt lgkmcnt(0)
	v_pk_mul_f32 v[42:43], v[68:69], v[42:43]
	s_nop 0
	v_cndmask_b32_e64 v43, -v43, v43, s[36:37]
	v_pk_mul_f32 v[62:63], v[64:65], v[62:63]
	v_cndmask_b32_e64 v42, -v42, v42, s[36:37]
	v_cndmask_b32_e64 v63, -v63, v63, s[36:37]
	v_cndmask_b32_e64 v62, -v62, v62, s[36:37]
	v_pk_fma_f32 v[54:55], v[54:55], v[60:61], v[62:63]
	v_pk_fma_f32 v[52:53], v[52:53], v[56:57], v[42:43]
	v_mov_b32_e32 v236, v48
	v_mov_b32_e32 v237, v48
	v_mov_b32_e32 v238, v49
	v_mov_b32_e32 v239, v49
	v_mov_b32_e32 v240, v50
	v_mov_b32_e32 v241, v50
	v_mov_b32_e32 v242, v51
	v_mov_b32_e32 v243, v51
	v_permlane32_swap_b32_e32 v236, v237
	v_permlane32_swap_b32_e32 v238, v239
	v_permlane32_swap_b32_e32 v240, v241
	v_permlane32_swap_b32_e32 v242, v243
	s_nop 0
	v_cndmask_b32_e64 v42, v237, v236, s[36:37]
	v_cndmask_b32_e64 v43, v239, v238, s[36:37]
	v_cndmask_b32_e64 v62, v241, v240, s[36:37]
	v_cndmask_b32_e64 v63, v243, v242, s[36:37]
	s_waitcnt lgkmcnt(0)
	v_pk_mul_f32 v[42:43], v[46:47], v[42:43]
	s_nop 0
	v_cndmask_b32_e64 v43, -v43, v43, s[36:37]
	v_pk_mul_f32 v[62:63], v[58:59], v[62:63]
	v_cndmask_b32_e64 v42, -v42, v42, s[36:37]
	v_cndmask_b32_e64 v63, -v63, v63, s[36:37]
	v_cndmask_b32_e64 v62, -v62, v62, s[36:37]
	v_pk_fma_f32 v[50:51], v[50:51], v[44:45], v[62:63]
	v_pk_fma_f32 v[48:49], v[48:49], v[40:41], v[42:43]

.LBB0_544:
	s_and_b64 vcc, exec, s[40:41]
	s_cbranch_vccnz .LBB0_546
	v_mbcnt_hi_u32_b32 v48, -1, v194
	v_and_b32_e32 v50, 64, v48
	v_xor_b32_e32 v49, 32, v48
	v_add_u32_e32 v50, 64, v50
	v_cmp_lt_i32_e32 vcc, v49, v50
	s_nop 1
	v_cndmask_b32_e32 v48, v48, v49, vcc
	v_lshlrev_b32_e32 v52, 2, v48
	v_mov_b32_e32 v236, v36
	v_mov_b32_e32 v237, v36
	v_mov_b32_e32 v238, v37
	v_mov_b32_e32 v239, v37
	v_mov_b32_e32 v240, v38
	v_mov_b32_e32 v241, v38
	v_mov_b32_e32 v242, v39
	v_mov_b32_e32 v243, v39
	v_permlane32_swap_b32_e32 v236, v237
	v_permlane32_swap_b32_e32 v238, v239
	v_permlane32_swap_b32_e32 v240, v241
	v_permlane32_swap_b32_e32 v242, v243
	s_nop 0
	v_cndmask_b32_e64 v48, v237, v236, s[36:37]
	v_cndmask_b32_e64 v49, v239, v238, s[36:37]
	v_cndmask_b32_e64 v50, v241, v240, s[36:37]
	v_cndmask_b32_e64 v51, v243, v242, s[36:37]
	s_waitcnt lgkmcnt(0)
	v_pk_mul_f32 v[48:49], v[68:69], v[48:49]
	s_nop 0
	v_cndmask_b32_e64 v49, -v49, v49, s[36:37]
	v_pk_mul_f32 v[50:51], v[64:65], v[50:51]
	v_cndmask_b32_e64 v48, -v48, v48, s[36:37]
	v_cndmask_b32_e64 v51, -v51, v51, s[36:37]
	v_cndmask_b32_e64 v50, -v50, v50, s[36:37]
	v_pk_fma_f32 v[38:39], v[38:39], v[60:61], v[50:51]
	v_pk_fma_f32 v[36:37], v[36:37], v[56:57], v[48:49]
	v_mov_b32_e32 v236, v32
	v_mov_b32_e32 v237, v32
	v_mov_b32_e32 v238, v33
	v_mov_b32_e32 v239, v33
	v_mov_b32_e32 v240, v34
	v_mov_b32_e32 v241, v34
	v_mov_b32_e32 v242, v35
	v_mov_b32_e32 v243, v35
	v_permlane32_swap_b32_e32 v236, v237
	v_permlane32_swap_b32_e32 v238, v239
	v_permlane32_swap_b32_e32 v240, v241
	v_permlane32_swap_b32_e32 v242, v243
	s_nop 0
	v_cndmask_b32_e64 v48, v237, v236, s[36:37]
	v_cndmask_b32_e64 v49, v239, v238, s[36:37]
	v_cndmask_b32_e64 v50, v241, v240, s[36:37]
	v_cndmask_b32_e64 v51, v243, v242, s[36:37]
	s_waitcnt lgkmcnt(0)
	v_pk_mul_f32 v[48:49], v[46:47], v[48:49]
	s_nop 0
	v_cndmask_b32_e64 v49, -v49, v49, s[36:37]
	v_pk_mul_f32 v[50:51], v[58:59], v[50:51]
	v_cndmask_b32_e64 v48, -v48, v48, s[36:37]
	v_cndmask_b32_e64 v51, -v51, v51, s[36:37]
	v_cndmask_b32_e64 v50, -v50, v50, s[36:37]
	v_pk_fma_f32 v[34:35], v[34:35], v[44:45], v[50:51]
	v_pk_fma_f32 v[32:33], v[32:33], v[40:41], v[48:49]

.LBB0_549:
	v_mbcnt_hi_u32_b32 v32, -1, v194
	v_and_b32_e32 v35, 64, v32
	v_xor_b32_e32 v33, 32, v32
	v_add_u32_e32 v35, 64, v35
	v_cmp_lt_i32_e32 vcc, v33, v35
	s_nop 1
	v_cndmask_b32_e32 v32, v32, v33, vcc
	v_lshlrev_b32_e32 v35, 2, v32
	v_mov_b32_e32 v236, v28
	v_mov_b32_e32 v237, v28
	v_mov_b32_e32 v238, v29
	v_mov_b32_e32 v239, v29
	v_mov_b32_e32 v240, v30
	v_mov_b32_e32 v241, v30
	v_mov_b32_e32 v242, v31
	v_mov_b32_e32 v243, v31
	v_permlane32_swap_b32_e32 v236, v237
	v_permlane32_swap_b32_e32 v238, v239
	v_permlane32_swap_b32_e32 v240, v241
	v_permlane32_swap_b32_e32 v242, v243
	s_nop 0
	v_cndmask_b32_e64 v32, v237, v236, s[36:37]
	v_cndmask_b32_e64 v33, v239, v238, s[36:37]
	v_cndmask_b32_e64 v36, v241, v240, s[36:37]
	v_cndmask_b32_e64 v37, v243, v242, s[36:37]
	s_waitcnt lgkmcnt(0)
	v_pk_mul_f32 v[32:33], v[68:69], v[32:33]
	s_nop 0
	v_cndmask_b32_e64 v33, -v33, v33, s[36:37]
	v_pk_mul_f32 v[36:37], v[64:65], v[36:37]
	v_cndmask_b32_e64 v32, -v32, v32, s[36:37]
	v_cndmask_b32_e64 v37, -v37, v37, s[36:37]
	v_cndmask_b32_e64 v36, -v36, v36, s[36:37]
	v_pk_fma_f32 v[30:31], v[30:31], v[60:61], v[36:37]
	v_pk_fma_f32 v[28:29], v[28:29], v[56:57], v[32:33]
	v_mov_b32_e32 v236, v24
	v_mov_b32_e32 v237, v24
	v_mov_b32_e32 v238, v25
	v_mov_b32_e32 v239, v25
	v_mov_b32_e32 v240, v26
	v_mov_b32_e32 v241, v26
	v_mov_b32_e32 v242, v27
	v_mov_b32_e32 v243, v27
	v_permlane32_swap_b32_e32 v236, v237
	v_permlane32_swap_b32_e32 v238, v239
	v_permlane32_swap_b32_e32 v240, v241
	v_permlane32_swap_b32_e32 v242, v243
	s_nop 0
	v_cndmask_b32_e64 v32, v237, v236, s[36:37]
	v_cndmask_b32_e64 v33, v239, v238, s[36:37]
	v_cndmask_b32_e64 v36, v241, v240, s[36:37]
	v_cndmask_b32_e64 v37, v243, v242, s[36:37]
	s_waitcnt lgkmcnt(0)
	v_pk_mul_f32 v[32:33], v[46:47], v[32:33]
	s_nop 0
	v_cndmask_b32_e64 v33, -v33, v33, s[36:37]
	v_pk_mul_f32 v[36:37], v[58:59], v[36:37]
	v_cndmask_b32_e64 v32, -v32, v32, s[36:37]
	v_cndmask_b32_e64 v37, -v37, v37, s[36:37]
	v_cndmask_b32_e64 v36, -v36, v36, s[36:37]
	v_pk_fma_f32 v[26:27], v[26:27], v[44:45], v[36:37]
	v_pk_fma_f32 v[24:25], v[24:25], v[40:41], v[32:33]

.LBB0_552:
	s_and_b64 vcc, exec, s[40:41]
	s_cbranch_vccnz .LBB0_554
	v_mbcnt_hi_u32_b32 v24, -1, v194
	v_and_b32_e32 v26, 64, v24
	v_xor_b32_e32 v25, 32, v24
	v_add_u32_e32 v26, 64, v26
	v_cmp_lt_i32_e32 vcc, v25, v26
	s_nop 1
	v_cndmask_b32_e32 v24, v24, v25, vcc
	v_lshlrev_b32_e32 v28, 2, v24
	v_mov_b32_e32 v236, v20
	v_mov_b32_e32 v237, v20
	v_mov_b32_e32 v238, v21
	v_mov_b32_e32 v239, v21
	v_mov_b32_e32 v240, v22
	v_mov_b32_e32 v241, v22
	v_mov_b32_e32 v242, v23
	v_mov_b32_e32 v243, v23
	v_permlane32_swap_b32_e32 v236, v237
	v_permlane32_swap_b32_e32 v238, v239
	v_permlane32_swap_b32_e32 v240, v241
	v_permlane32_swap_b32_e32 v242, v243
	s_nop 0
	v_cndmask_b32_e64 v24, v237, v236, s[36:37]
	v_cndmask_b32_e64 v25, v239, v238, s[36:37]
	v_cndmask_b32_e64 v26, v241, v240, s[36:37]
	v_cndmask_b32_e64 v27, v243, v242, s[36:37]
	s_waitcnt lgkmcnt(0)
	v_pk_mul_f32 v[24:25], v[68:69], v[24:25]
	s_nop 0
	v_cndmask_b32_e64 v25, -v25, v25, s[36:37]
	v_pk_mul_f32 v[26:27], v[64:65], v[26:27]
	v_cndmask_b32_e64 v24, -v24, v24, s[36:37]
	v_cndmask_b32_e64 v27, -v27, v27, s[36:37]
	v_cndmask_b32_e64 v26, -v26, v26, s[36:37]
	v_pk_fma_f32 v[22:23], v[22:23], v[60:61], v[26:27]
	v_pk_fma_f32 v[20:21], v[20:21], v[56:57], v[24:25]
	v_mov_b32_e32 v236, v16
	v_mov_b32_e32 v237, v16
	v_mov_b32_e32 v238, v17
	v_mov_b32_e32 v239, v17
	v_mov_b32_e32 v240, v18
	v_mov_b32_e32 v241, v18
	v_mov_b32_e32 v242, v19
	v_mov_b32_e32 v243, v19
	v_permlane32_swap_b32_e32 v236, v237
	v_permlane32_swap_b32_e32 v238, v239
	v_permlane32_swap_b32_e32 v240, v241
	v_permlane32_swap_b32_e32 v242, v243
	s_nop 0
	v_cndmask_b32_e64 v24, v237, v236, s[36:37]
	v_cndmask_b32_e64 v25, v239, v238, s[36:37]
	v_cndmask_b32_e64 v26, v241, v240, s[36:37]
	v_cndmask_b32_e64 v27, v243, v242, s[36:37]
	s_waitcnt lgkmcnt(0)
	v_pk_mul_f32 v[24:25], v[46:47], v[24:25]
	s_nop 0
	v_cndmask_b32_e64 v25, -v25, v25, s[36:37]
	v_pk_mul_f32 v[26:27], v[58:59], v[26:27]
	v_cndmask_b32_e64 v24, -v24, v24, s[36:37]
	v_cndmask_b32_e64 v27, -v27, v27, s[36:37]
	v_cndmask_b32_e64 v26, -v26, v26, s[36:37]
	v_pk_fma_f32 v[18:19], v[18:19], v[44:45], v[26:27]
	v_pk_fma_f32 v[16:17], v[16:17], v[40:41], v[24:25]

.LBB0_557:
	v_mbcnt_hi_u32_b32 v16, -1, v194
	v_and_b32_e32 v19, 64, v16
	v_xor_b32_e32 v17, 32, v16
	v_add_u32_e32 v19, 64, v19
	v_cmp_lt_i32_e32 vcc, v17, v19
	s_nop 1
	v_cndmask_b32_e32 v16, v16, v17, vcc
	v_lshlrev_b32_e32 v19, 2, v16
	v_mov_b32_e32 v236, v12
	v_mov_b32_e32 v237, v12
	v_mov_b32_e32 v238, v13
	v_mov_b32_e32 v239, v13
	v_mov_b32_e32 v240, v14
	v_mov_b32_e32 v241, v14
	v_mov_b32_e32 v242, v15
	v_mov_b32_e32 v243, v15
	v_permlane32_swap_b32_e32 v236, v237
	v_permlane32_swap_b32_e32 v238, v239
	v_permlane32_swap_b32_e32 v240, v241
	v_permlane32_swap_b32_e32 v242, v243
	s_nop 0
	v_cndmask_b32_e64 v16, v237, v236, s[36:37]
	v_cndmask_b32_e64 v17, v239, v238, s[36:37]
	v_cndmask_b32_e64 v20, v241, v240, s[36:37]
	v_cndmask_b32_e64 v21, v243, v242, s[36:37]
	s_waitcnt lgkmcnt(0)
	v_pk_mul_f32 v[16:17], v[68:69], v[16:17]
	s_nop 0
	v_cndmask_b32_e64 v17, -v17, v17, s[36:37]
	v_pk_mul_f32 v[20:21], v[64:65], v[20:21]
	v_cndmask_b32_e64 v16, -v16, v16, s[36:37]
	v_cndmask_b32_e64 v21, -v21, v21, s[36:37]
	v_cndmask_b32_e64 v20, -v20, v20, s[36:37]
	v_pk_fma_f32 v[14:15], v[14:15], v[60:61], v[20:21]
	v_pk_fma_f32 v[12:13], v[12:13], v[56:57], v[16:17]
	v_mov_b32_e32 v236, v8
	v_mov_b32_e32 v237, v8
	v_mov_b32_e32 v238, v9
	v_mov_b32_e32 v239, v9
	v_mov_b32_e32 v240, v10
	v_mov_b32_e32 v241, v10
	v_mov_b32_e32 v242, v11
	v_mov_b32_e32 v243, v11
	v_permlane32_swap_b32_e32 v236, v237
	v_permlane32_swap_b32_e32 v238, v239
	v_permlane32_swap_b32_e32 v240, v241
	v_permlane32_swap_b32_e32 v242, v243
	s_nop 0
	v_cndmask_b32_e64 v16, v237, v236, s[36:37]
	v_cndmask_b32_e64 v17, v239, v238, s[36:37]
	v_cndmask_b32_e64 v20, v241, v240, s[36:37]
	v_cndmask_b32_e64 v21, v243, v242, s[36:37]
	s_waitcnt lgkmcnt(0)
	v_pk_mul_f32 v[16:17], v[46:47], v[16:17]
	s_nop 0
	v_cndmask_b32_e64 v17, -v17, v17, s[36:37]
	v_pk_mul_f32 v[20:21], v[58:59], v[20:21]
	v_cndmask_b32_e64 v16, -v16, v16, s[36:37]
	v_cndmask_b32_e64 v21, -v21, v21, s[36:37]
	v_cndmask_b32_e64 v20, -v20, v20, s[36:37]
	v_pk_fma_f32 v[10:11], v[10:11], v[44:45], v[20:21]
	v_pk_fma_f32 v[8:9], v[8:9], v[40:41], v[16:17]

.LBB0_560:
	s_and_b64 vcc, exec, s[40:41]
	s_cbranch_vccnz .LBB0_562
	v_mbcnt_hi_u32_b32 v8, -1, v194
	v_and_b32_e32 v10, 64, v8
	v_xor_b32_e32 v9, 32, v8
	v_add_u32_e32 v10, 64, v10
	v_cmp_lt_i32_e32 vcc, v9, v10
	s_nop 1
	v_cndmask_b32_e32 v8, v8, v9, vcc
	v_lshlrev_b32_e32 v12, 2, v8
	v_mov_b32_e32 v236, v4
	v_mov_b32_e32 v237, v4
	v_mov_b32_e32 v238, v5
	v_mov_b32_e32 v239, v5
	v_mov_b32_e32 v240, v6
	v_mov_b32_e32 v241, v6
	v_mov_b32_e32 v242, v7
	v_mov_b32_e32 v243, v7
	v_permlane32_swap_b32_e32 v236, v237
	v_permlane32_swap_b32_e32 v238, v239
	v_permlane32_swap_b32_e32 v240, v241
	v_permlane32_swap_b32_e32 v242, v243
	s_nop 0
	v_cndmask_b32_e64 v8, v237, v236, s[36:37]
	v_cndmask_b32_e64 v9, v239, v238, s[36:37]
	v_cndmask_b32_e64 v10, v241, v240, s[36:37]
	v_cndmask_b32_e64 v11, v243, v242, s[36:37]
	s_waitcnt lgkmcnt(0)
	v_pk_mul_f32 v[8:9], v[68:69], v[8:9]
	s_nop 0
	v_cndmask_b32_e64 v9, -v9, v9, s[36:37]
	v_pk_mul_f32 v[10:11], v[64:65], v[10:11]
	v_cndmask_b32_e64 v8, -v8, v8, s[36:37]
	v_cndmask_b32_e64 v11, -v11, v11, s[36:37]
	v_cndmask_b32_e64 v10, -v10, v10, s[36:37]
	v_pk_fma_f32 v[6:7], v[6:7], v[60:61], v[10:11]
	v_pk_fma_f32 v[4:5], v[4:5], v[56:57], v[8:9]
	v_mov_b32_e32 v236, v0
	v_mov_b32_e32 v237, v0
	v_mov_b32_e32 v238, v1
	v_mov_b32_e32 v239, v1
	v_mov_b32_e32 v240, v2
	v_mov_b32_e32 v241, v2
	v_mov_b32_e32 v242, v3
	v_mov_b32_e32 v243, v3
	v_permlane32_swap_b32_e32 v236, v237
	v_permlane32_swap_b32_e32 v238, v239
	v_permlane32_swap_b32_e32 v240, v241
	v_permlane32_swap_b32_e32 v242, v243
	s_nop 0
	v_cndmask_b32_e64 v8, v237, v236, s[36:37]
	v_cndmask_b32_e64 v9, v239, v238, s[36:37]
	v_cndmask_b32_e64 v10, v241, v240, s[36:37]
	v_cndmask_b32_e64 v11, v243, v242, s[36:37]
	s_waitcnt lgkmcnt(0)
	v_pk_mul_f32 v[8:9], v[46:47], v[8:9]
	s_nop 0
	v_cndmask_b32_e64 v9, -v9, v9, s[36:37]
	v_pk_mul_f32 v[10:11], v[58:59], v[10:11]
	v_cndmask_b32_e64 v8, -v8, v8, s[36:37]
	v_cndmask_b32_e64 v11, -v11, v11, s[36:37]
	v_cndmask_b32_e64 v10, -v10, v10, s[36:37]
	v_pk_fma_f32 v[2:3], v[2:3], v[44:45], v[10:11]
	v_pk_fma_f32 v[0:1], v[0:1], v[40:41], v[8:9]
